# v32 plus one static s_setprio 1 for waves 4-7 during phases 2 (retention/SWA) and 7 (cross-attention), reset to 0 at phase end
# baseline (speedup 1.0000x reference)
; __global__ void __launch_bounds__(512, 2) fwd_mega(Params p) {
;     ...
;     if (IN(2)) {
;         swa_build_bias(p, L, tid);
.LBB0_516:
	s_cmp_lt_i32 s66, 3
	s_cselect_b64 s[0:1], -1, 0
	s_and_b64 s[0:1], s[0:1], s[2:3]
	v_writelane_b32 v254, s0, 24
	s_andn2_b64 vcc, exec, s[0:1]
	s_nop 0
	v_writelane_b32 v254, s1, 25
	s_cbranch_vccnz .LBB0_633
	v_readfirstlane_b32 s98, v153
	s_nop 0
	s_and_b32 s98, s98, 0x100
	s_cmp_lg_u32 s98, 0
	s_cbranch_scc0 .Lprio2_skip
	s_setprio 1

; DI unsigned xb_ld(unsigned* p)              { return __hip_atomic_load(p, __ATOMIC_RELAXED, __HIP_MEMORY_SCOPE_AGENT); }
; #define SEAM(k) do { if (IN(k) && IN((k) + 1)) xcd_barrier(xbar); } while (0)
; DI void xcd_barrier_complete(unsigned* bar, unsigned x, unsigned& nloc, unsigned& nx) {
;     const unsigned G = gridDim.x * gridDim.y * gridDim.z;
;     unsigned sum, cnt, mine, sp = 0u;
;     for (;;) {
;         sum = 0u; cnt = 0u; mine = 0u;
; #pragma unroll
;         for (unsigned j = 0; j < 16; ++j) { const unsigned c = xb_ld(&bar[XB_XCNT(j)]); sum += c; cnt += (c > 0u) ? 1u : 0u; mine = (j == x) ? c : mine; }
; DI void xcd_barrier(const XcdBarrier& b) {
;     asm volatile("s_waitcnt vmcnt(0)" ::: "memory");
;     __syncthreads();
;     if (threadIdx.x == 0) {
;         unsigned* bar = b.bar;
;         __builtin_amdgcn_s_waitcnt(0);
;         unsigned nloc = b.st[0], nx = b.st[1];
;         if (nloc == 0u) { xcd_barrier_complete(bar, b.x, nloc, nx); b.st[0] = nloc; b.st[1] = nx; }
; __global__ void __launch_bounds__(512, 2) fwd_mega(Params p) {
;     ...
;     SEAM(2);
;     if (IN(3)) {
.LBB0_633:
	s_setprio 0
	s_cmp_gt_i32 s67, 3
	v_readlane_b32 s2, v254, 24
	s_cselect_b64 s[0:1], -1, 0
	v_readlane_b32 s3, v254, 25
	s_and_b64 s[2:3], s[2:3], s[0:1]
	s_andn2_b64 vcc, exec, s[2:3]
	s_cbranch_vccnz .LBB0_687
	s_waitcnt vmcnt(0)
	s_waitcnt vmcnt(0)
	s_barrier
	s_mov_b64 s[2:3], exec
	v_readlane_b32 s4, v254, 5
	v_readlane_b32 s5, v254, 6
	s_and_b64 s[4:5], s[2:3], s[4:5]
	s_mov_b64 exec, s[4:5]
	s_cbranch_execz .LBB0_686
	s_add_i32 s4, 0, 0x22800
	v_mov_b32_e32 v0, s4
	s_waitcnt vmcnt(0) expcnt(0) lgkmcnt(0)
	ds_read_b32 v2, v0
	s_add_i32 s4, 0, 0x22804
	v_mov_b32_e32 v0, s4
	ds_read_b32 v0, v0
	s_waitcnt lgkmcnt(1)
	v_cmp_ne_u32_e32 vcc, 0, v2
	s_cbranch_vccnz .LBB0_650
	v_readlane_b32 s4, v254, 0
	v_readlane_b32 s5, v254, 1
	s_load_dwordx2 s[8:9], s[4:5], 0x4
	s_add_u32 s4, s94, 0x1d0200
	s_addc_u32 s5, s95, 0
	s_add_u32 s6, s94, 0x1d0400
	s_addc_u32 s7, s95, 0
	s_waitcnt lgkmcnt(0)
	s_mul_i32 s33, s8, s65
	s_add_u32 s8, s94, 0x1d0500
	s_mul_i32 s33, s33, s9
	s_addc_u32 s9, s95, 0
	s_add_u32 s10, s94, 0x1d0600
	s_addc_u32 s11, s95, 0
	s_add_u32 s12, s94, 0x1d0700
	s_addc_u32 s13, s95, 0
	s_add_u32 s14, s94, 0x1d0800
	s_addc_u32 s15, s95, 0
	s_add_u32 s16, s94, 0x1d0900
	s_addc_u32 s17, s95, 0
	s_add_u32 s18, s94, 0x1d0a00
	s_addc_u32 s19, s95, 0
	s_add_u32 s20, s94, 0x1d0b00
	s_addc_u32 s21, s95, 0
	s_add_u32 s22, s94, 0x1d0c00
	s_addc_u32 s23, s95, 0
	s_add_u32 s24, s94, 0x1d0d00
	s_addc_u32 s25, s95, 0
	s_add_u32 s26, s94, 0x1d0e00
	s_addc_u32 s27, s95, 0
	s_add_u32 s28, s94, 0x1d0f00
	s_addc_u32 s29, s95, 0
	s_add_u32 s30, s94, 0x1d1000
	s_addc_u32 s31, s95, 0
	s_add_u32 s34, s94, 0x1d1100
	s_addc_u32 s35, s95, 0
	s_add_u32 s36, s94, 0x1d1200
	s_addc_u32 s37, s95, 0
	s_add_u32 s38, s94, 0x1d1300
	s_addc_u32 s39, s95, 0
	s_mov_b32 s46, 1
	v_mov_b32_e32 v16, 0
	s_branch .LBB0_638

; __global__ void __launch_bounds__(512, 2) fwd_mega(Params p) {
;     ...
;     if (IN(7)) {
;     ...
;         cross_phase(p, L, tid, lane, wave, true);
;     ...
;         cross_phase(p, L, tid, lane, wave, true, 1);
;     ...
;         cross_phase(p, L, tid, lane, wave, true, 2);
;     ...
;         cross_phase(p, L, tid, lane, wave); }
.LBB0_1051:
	s_cmp_lt_i32 s66, 8
	s_cselect_b64 s[2:3], -1, 0
	s_and_b64 s[0:1], s[2:3], s[0:1]
	s_andn2_b64 vcc, exec, s[0:1]
	s_cbranch_vccnz .LBB0_1094
	v_readfirstlane_b32 s98, v153
	s_nop 0
	s_and_b32 s98, s98, 0x100
	s_cmp_lg_u32 s98, 0
	s_cbranch_scc0 .Lprio7_skip
	s_setprio 1

; #define SEAM(k) do { if (IN(k) && IN((k) + 1)) xcd_barrier(xbar); } while (0)
; DI void xcd_barrier(const XcdBarrier& b) {
;     asm volatile("s_waitcnt vmcnt(0)" ::: "memory");
;     __syncthreads();
;     if (threadIdx.x == 0) {
;         unsigned* bar = b.bar;
;         __builtin_amdgcn_s_waitcnt(0);
;         unsigned nloc = b.st[0], nx = b.st[1];
;         if (nloc == 0u) { xcd_barrier_complete(bar, b.x, nloc, nx); b.st[0] = nloc; b.st[1] = nx; }
; __global__ void __launch_bounds__(512, 2) fwd_mega(Params p) {
;     ...
;     SEAM(7);
.LBB0_1094:
	s_setprio 0
	s_cmp_gt_i32 s67, 8
	s_cselect_b64 s[2:3], -1, 0
	s_and_b64 s[0:1], s[0:1], s[2:3]
	s_andn2_b64 vcc, exec, s[0:1]
	s_cbranch_vccnz .LBB0_1148
	s_waitcnt vmcnt(0)
	s_waitcnt vmcnt(0) lgkmcnt(0)
	s_barrier
	s_mov_b64 s[0:1], exec
	v_readlane_b32 s4, v254, 5
	v_readlane_b32 s5, v254, 6
	s_and_b64 s[4:5], s[0:1], s[4:5]
	s_mov_b64 exec, s[4:5]
	s_cbranch_execz .LBB0_1147
	s_add_i32 s4, 0, 0x22800
	v_mov_b32_e32 v0, s4
	s_waitcnt vmcnt(0) expcnt(0) lgkmcnt(0)
	ds_read_b32 v2, v0
	s_add_i32 s4, 0, 0x22804
	v_mov_b32_e32 v0, s4
	ds_read_b32 v0, v0
	s_waitcnt lgkmcnt(1)
	v_cmp_ne_u32_e32 vcc, 0, v2
	s_cbranch_vccnz .LBB0_1111
	v_readlane_b32 s4, v254, 0
	v_readlane_b32 s5, v254, 1
	s_load_dwordx2 s[8:9], s[4:5], 0x4
	s_add_u32 s4, s94, 0x1d0200
	s_addc_u32 s5, s95, 0
	s_add_u32 s6, s94, 0x1d0400
	s_addc_u32 s7, s95, 0
	s_waitcnt lgkmcnt(0)
	s_mul_i32 s33, s8, s65
	s_add_u32 s8, s94, 0x1d0500
	s_mul_i32 s33, s33, s9
	s_addc_u32 s9, s95, 0
	s_add_u32 s10, s94, 0x1d0600
	s_addc_u32 s11, s95, 0
	s_add_u32 s12, s94, 0x1d0700
	s_addc_u32 s13, s95, 0
	s_add_u32 s14, s94, 0x1d0800
	s_addc_u32 s15, s95, 0
	s_add_u32 s16, s94, 0x1d0900
	s_addc_u32 s17, s95, 0
	s_add_u32 s18, s94, 0x1d0a00
	s_addc_u32 s19, s95, 0
	s_add_u32 s20, s94, 0x1d0b00
	s_addc_u32 s21, s95, 0
	s_add_u32 s22, s94, 0x1d0c00
	s_addc_u32 s23, s95, 0
	s_add_u32 s24, s94, 0x1d0d00
	s_addc_u32 s25, s95, 0
	s_add_u32 s26, s94, 0x1d0e00
	s_addc_u32 s27, s95, 0
	s_add_u32 s28, s94, 0x1d0f00
	s_addc_u32 s29, s95, 0
	s_add_u32 s30, s94, 0x1d1000
	s_addc_u32 s31, s95, 0
	s_add_u32 s34, s94, 0x1d1100
	s_addc_u32 s35, s95, 0
	s_add_u32 s36, s94, 0x1d1200
	s_addc_u32 s37, s95, 0
	s_add_u32 s38, s94, 0x1d1300
	s_addc_u32 s39, s95, 0
	s_mov_b32 s46, 1
	v_mov_b32_e32 v16, 0
	s_branch .LBB0_1099
